# DK=96 attention tile loop unrolled by the ring depth: K/V fragment and LDS-DMA ring stages as immediates, per-tile address VALU and readfirstlane chain removed
# baseline (speedup 1.0000x reference)
.LBB0_372:
	v_and_b32_e32 v4, 15, v22
	v_bitop3_b32 v6, v23, v22, 15 bitop3:0x78
	v_lshlrev_b32_e32 v115, 4, v6
	v_bitop3_b32 v6, v23, v4, 2 bitop3:0x36
	v_lshlrev_b32_e32 v116, 4, v6
	v_bitop3_b32 v6, v23, v4, 4 bitop3:0x36
	v_lshlrev_b32_e32 v117, 4, v6
	v_bitop3_b32 v6, v23, v4, 6 bitop3:0x36
	v_lshlrev_b32_e32 v118, 4, v6
	v_bitop3_b32 v6, v23, v4, 8 bitop3:0x36
	v_bitop3_b32 v4, v23, v4, 10 bitop3:0x36
	v_lshlrev_b32_e32 v120, 4, v4
	v_lshlrev_b32_e32 v4, 3, v22
	s_movk_i32 s3, 0x50
	v_bitop3_b32 v126, v4, s3, v235 bitop3:0x6c
	s_movk_i32 s3, 0x60
	v_bitop3_b32 v127, v4, s3, v235 bitop3:0x6c
	s_movk_i32 s3, 0x70
	v_lshlrev_b32_e32 v5, 7, v24
	v_bitop3_b32 v128, v4, s3, v4 bitop3:0xc
	s_mov_b32 s3, 0x10000
	v_mov_b32_e32 v18, v3
	v_mov_b32_e32 v19, v3
	v_lshlrev_b32_e32 v103, 8, v24
	v_lshlrev_b32_e32 v119, 4, v6
	v_and_b32_e32 v121, 0x70, v4
	v_bitop3_b32 v122, v4, 16, v235 bitop3:0x6c
	v_bitop3_b32 v123, v4, 32, v235 bitop3:0x6c
	v_bitop3_b32 v124, v4, 48, v235 bitop3:0x6c
	v_bitop3_b32 v125, v4, 64, v235 bitop3:0x6c
	v_or3_b32 v129, v5, v98, s3
	v_mov_b32_e32 v4, v3
	v_mov_b32_e32 v5, v3
	v_mov_b32_e32 v6, v3
	v_mov_b32_e32 v7, v3
	v_mov_b32_e32 v8, v3
	v_mov_b32_e32 v9, v3
	v_mov_b32_e32 v10, v3
	v_mov_b32_e32 v11, v3
	v_mov_b32_e32 v12, v3
	v_mov_b32_e32 v13, v3
	v_mov_b32_e32 v14, v3
	v_mov_b32_e32 v15, v3
	v_mov_b32_e32 v16, v3
	v_mov_b32_e32 v17, v3
	v_mov_b64_e32 v[34:35], v[18:19]
	s_add_i32 s5, s2, -3
	s_add_i32 s26, s2, -1
	s_mov_b32 s27, 0
	v_mov_b32_e32 v131, 0xf149f2ca
	v_mov_b32_e32 v130, 0
	v_mov_b64_e32 v[32:33], v[16:17]
	v_mov_b64_e32 v[30:31], v[14:15]
	v_mov_b64_e32 v[28:29], v[12:13]
	v_mov_b64_e32 v[26:27], v[10:11]
	v_mov_b64_e32 v[24:25], v[8:9]
	v_mov_b64_e32 v[22:23], v[6:7]
	v_mov_b64_e32 v[20:21], v[4:5]
	v_add_u32_e32 v194, v103, v115
	v_add_u32_e32 v195, v103, v116
	v_add_u32_e32 v196, v103, v117
	v_add_u32_e32 v197, v103, v118
	v_add_u32_e32 v198, v103, v119
	v_add_u32_e32 v199, v103, v120
	v_add_u32_e32 v200, v129, v121
	v_add_u32_e32 v201, v129, v122
	v_add_u32_e32 v202, v129, v123
	v_add_u32_e32 v203, v129, v124
	v_add_u32_e32 v204, v129, v125
	v_add_u32_e32 v205, v129, v126
	v_add_u32_e32 v206, v129, v127
	v_add_u32_e32 v207, v129, v128
	v_readfirstlane_b32 s98, v99
	v_readfirstlane_b32 s99, v101
	s_cmp_lt_i32 s26, 2
	s_mov_b64 s[2:3], -1
	s_cbranch_scc0 .LBB0_379
	s_branch .LBB0_374

.LBB0_383:
	ds_read_b128 v[132:135], v194
	ds_read_b128 v[136:139], v195
	ds_read_b128 v[140:143], v196
	ds_read_b128 v[144:147], v197
	ds_read_b128 v[148:151], v198
	ds_read_b128 v[152:155], v199
	ds_read_b128 v[156:159], v194 offset:8192
	ds_read_b128 v[160:163], v195 offset:8192
	ds_read_b128 v[164:167], v196 offset:8192
	ds_read_b128 v[168:171], v197 offset:8192
	ds_read_b128 v[172:175], v198 offset:8192
	ds_read_b128 v[176:179], v199 offset:8192
	s_waitcnt lgkmcnt(11)
	v_mfma_f32_32x32x16_bf16 v[52:67], v[132:135], v[68:71], 0
	s_waitcnt lgkmcnt(10)
	v_mfma_f32_32x32x16_bf16 v[52:67], v[136:139], v[72:75], v[52:67]
	s_waitcnt lgkmcnt(9)
	v_mfma_f32_32x32x16_bf16 v[52:67], v[140:143], v[76:79], v[52:67]
	s_waitcnt lgkmcnt(8)
	v_mfma_f32_32x32x16_bf16 v[52:67], v[144:147], v[80:83], v[52:67]
	s_waitcnt lgkmcnt(7)
	v_mfma_f32_32x32x16_bf16 v[52:67], v[148:151], v[84:87], v[52:67]
	s_waitcnt lgkmcnt(6)
	v_mfma_f32_32x32x16_bf16 v[52:67], v[152:155], v[88:91], v[52:67]
	s_waitcnt lgkmcnt(0)
	v_mfma_f32_32x32x16_bf16 v[36:51], v[156:159], v[68:71], 0
	ds_read_b64 v[132:133], v200
	ds_read_b64 v[134:135], v201
	v_mfma_f32_32x32x16_bf16 v[36:51], v[160:163], v[72:75], v[36:51]
	ds_read_b64 v[136:137], v202
	ds_read_b64 v[138:139], v203
	v_mfma_f32_32x32x16_bf16 v[36:51], v[164:167], v[76:79], v[36:51]
	ds_read_b64 v[140:141], v204
	ds_read_b64 v[142:143], v205
	v_mfma_f32_32x32x16_bf16 v[36:51], v[168:171], v[80:83], v[36:51]
	ds_read_b64 v[144:145], v206
	ds_read_b64 v[146:147], v207
	v_mfma_f32_32x32x16_bf16 v[36:51], v[172:175], v[84:87], v[36:51]
	v_mfma_f32_32x32x16_bf16 v[36:51], v[176:179], v[88:91], v[36:51]
	ds_read_b64 v[156:157], v204 offset:4096
	ds_read_b64 v[158:159], v205 offset:4096
	ds_read_b64 v[160:161], v206 offset:4096
	ds_read_b64 v[162:163], v207 offset:4096
	ds_read_b64 v[152:153], v202 offset:4096
	ds_read_b64 v[154:155], v203 offset:4096
	ds_read_b64 v[148:149], v200 offset:4096
	ds_read_b64 v[150:151], v201 offset:4096
	v_max3_f32 v107, v52, v53, v54
	v_max3_f32 v107, v107, v55, v56
	v_max3_f32 v107, v107, v57, v58
	v_max3_f32 v107, v107, v59, v60
	v_max3_f32 v107, v107, v61, v62
	v_max3_f32 v107, v107, v63, v64
	v_max3_f32 v107, v107, v65, v66
	v_max_f32_e32 v107, v107, v67
	v_max3_f32 v114, v36, v37, v38
	v_max3_f32 v114, v114, v39, v40
	v_max3_f32 v114, v114, v41, v42
	v_max3_f32 v114, v114, v43, v44
	v_max3_f32 v114, v114, v45, v46
	v_max3_f32 v114, v114, v47, v48
	v_max3_f32 v114, v114, v49, v50
	v_max3_f32 v107, v107, v114, v51
	v_mul_f32_e32 v107, s33, v107
	v_mov_b32_e32 v172, v107
	s_nop 1
	v_permlane32_swap_b32 v107, v172
	s_nop 1
	v_max3_f32 v107, v131, v107, v172
	v_sub_f32_e32 v114, v131, v107
	v_exp_f32_e32 v114, v114
	v_cmp_neq_f32_e32 vcc, v107, v131
	s_cbranch_vccz .Lat96_keep
	v_pk_mul_f32 v[34:35], v[34:35], v[114:115] op_sel_hi:[1,0]
	v_pk_mul_f32 v[32:33], v[32:33], v[114:115] op_sel_hi:[1,0]
	v_pk_mul_f32 v[30:31], v[30:31], v[114:115] op_sel_hi:[1,0]
	v_pk_mul_f32 v[28:29], v[28:29], v[114:115] op_sel_hi:[1,0]
	v_pk_mul_f32 v[26:27], v[26:27], v[114:115] op_sel_hi:[1,0]
	v_pk_mul_f32 v[24:25], v[24:25], v[114:115] op_sel_hi:[1,0]
	v_pk_mul_f32 v[22:23], v[22:23], v[114:115] op_sel_hi:[1,0]
	v_pk_mul_f32 v[20:21], v[20:21], v[114:115] op_sel_hi:[1,0]
	v_pk_mul_f32 v[18:19], v[18:19], v[114:115] op_sel_hi:[1,0]
	v_pk_mul_f32 v[16:17], v[16:17], v[114:115] op_sel_hi:[1,0]
	v_pk_mul_f32 v[14:15], v[14:15], v[114:115] op_sel_hi:[1,0]
	v_pk_mul_f32 v[12:13], v[12:13], v[114:115] op_sel_hi:[1,0]
	v_pk_mul_f32 v[10:11], v[10:11], v[114:115] op_sel_hi:[1,0]
	v_pk_mul_f32 v[8:9], v[8:9], v[114:115] op_sel_hi:[1,0]
	v_pk_mul_f32 v[6:7], v[6:7], v[114:115] op_sel_hi:[1,0]
	v_pk_mul_f32 v[4:5], v[4:5], v[114:115] op_sel_hi:[1,0]
.Lat96_keep:
	v_fma_f32 v52, v52, s33, -v107
	v_fma_f32 v53, v53, s33, -v107
	v_fma_f32 v54, v54, s33, -v107
	v_fma_f32 v55, v55, s33, -v107
	v_fma_f32 v56, v56, s33, -v107
	v_fma_f32 v57, v57, s33, -v107
	v_fma_f32 v58, v58, s33, -v107
	v_fma_f32 v59, v59, s33, -v107
	v_exp_f32_e32 v52, v52
	v_exp_f32_e32 v53, v53
	v_exp_f32_e32 v54, v54
	v_exp_f32_e32 v55, v55
	v_exp_f32_e32 v56, v56
	v_exp_f32_e32 v57, v57
	v_exp_f32_e32 v58, v58
	v_exp_f32_e32 v59, v59
	v_cvt_pk_bf16_f32 v164, v52, v53
	v_cvt_pk_bf16_f32 v165, v54, v55
	v_cvt_pk_bf16_f32 v166, v56, v57
	v_cvt_pk_bf16_f32 v167, v58, v59
	v_add_f32_e32 v52, v52, v53
	v_add_f32_e32 v54, v54, v55
	v_add_f32_e32 v56, v56, v57
	v_add_f32_e32 v58, v58, v59
	v_add_f32_e32 v52, v52, v54
	v_add_f32_e32 v56, v56, v58
	v_add_f32_e32 v52, v52, v56
	s_cmp_ge_i32 s27, s5
	s_cbranch_scc1 .Lat96_nodma
	s_cmp_eq_u32 s4, s0
	s_cselect_b64 s[2:3], -1, 0
	s_and_b64 vcc, s[24:25], s[2:3]
	s_add_i32 m0, s98, 0xc000
	v_cndmask_b32_e32 v59, v109, v95, vcc
	v_cndmask_b32_e32 v58, v108, v94, vcc
	v_cndmask_b32_e32 v57, v111, v97, vcc
	v_cndmask_b32_e32 v56, v110, v96, vcc
	global_load_lds_dwordx4 v[58:59], off
	s_add_i32 m0, s98, 0xc400
	v_cndmask_b32_e32 v55, v113, v105, vcc
	v_cndmask_b32_e32 v54, v112, v104, vcc
	global_load_lds_dwordx4 v[56:57], off
	s_add_i32 m0, s99, 0x6000
	v_cndmask_b32_e32 v106, v106, v102, vcc
	global_load_lds_dwordx4 v[54:55], off
	v_cndmask_b32_e32 v2, v2, v100, vcc
	v_lshl_add_u64 v[108:109], v[2:3], 1, v[58:59]
	v_lshlrev_b32_e32 v53, 1, v106
	v_add_co_u32_e32 v110, vcc, v53, v56
	s_nop 1
	v_addc_co_u32_e32 v111, vcc, 0, v57, vcc
	v_lshl_add_u64 v[112:113], v[54:55], 0, s[82:83]
	s_add_i32 s4, s4, 1
.Lat96_nodma:
	v_fma_f32 v60, v60, s33, -v107
	v_fma_f32 v61, v61, s33, -v107
	v_fma_f32 v62, v62, s33, -v107
	v_fma_f32 v63, v63, s33, -v107
	v_fma_f32 v64, v64, s33, -v107
	v_fma_f32 v65, v65, s33, -v107
	v_fma_f32 v66, v66, s33, -v107
	v_fma_f32 v67, v67, s33, -v107
	v_exp_f32_e32 v60, v60
	v_exp_f32_e32 v61, v61
	v_exp_f32_e32 v62, v62
	v_exp_f32_e32 v63, v63
	v_exp_f32_e32 v64, v64
	v_exp_f32_e32 v65, v65
	v_exp_f32_e32 v66, v66
	v_exp_f32_e32 v67, v67
	v_cvt_pk_bf16_f32 v168, v60, v61
	v_cvt_pk_bf16_f32 v169, v62, v63
	v_cvt_pk_bf16_f32 v170, v64, v65
	v_cvt_pk_bf16_f32 v171, v66, v67
	v_add_f32_e32 v60, v60, v61
	v_add_f32_e32 v62, v62, v63
	v_add_f32_e32 v64, v64, v65
	v_add_f32_e32 v66, v66, v67
	v_add_f32_e32 v60, v60, v62
	v_add_f32_e32 v64, v64, v66
	v_add_f32_e32 v60, v60, v64
	s_waitcnt lgkmcnt(0)
	v_mfma_f32_32x32x16_bf16 v[20:35], v[132:135], v[164:167], v[20:35]
	v_fma_f32 v36, v36, s33, -v107
	v_fma_f32 v37, v37, s33, -v107
	v_fma_f32 v38, v38, s33, -v107
	v_fma_f32 v39, v39, s33, -v107
	v_fma_f32 v40, v40, s33, -v107
	v_fma_f32 v41, v41, s33, -v107
	v_fma_f32 v42, v42, s33, -v107
	v_fma_f32 v43, v43, s33, -v107
	v_mfma_f32_32x32x16_bf16 v[4:19], v[148:151], v[164:167], v[4:19]
	v_exp_f32_e32 v36, v36
	v_exp_f32_e32 v37, v37
	v_exp_f32_e32 v38, v38
	v_exp_f32_e32 v39, v39
	v_exp_f32_e32 v40, v40
	v_exp_f32_e32 v41, v41
	v_exp_f32_e32 v42, v42
	v_exp_f32_e32 v43, v43
	v_mfma_f32_32x32x16_bf16 v[20:35], v[136:139], v[168:171], v[20:35]
	v_cvt_pk_bf16_f32 v172, v36, v37
	v_cvt_pk_bf16_f32 v173, v38, v39
	v_cvt_pk_bf16_f32 v174, v40, v41
	v_cvt_pk_bf16_f32 v175, v42, v43
	v_add_f32_e32 v36, v36, v37
	v_add_f32_e32 v38, v38, v39
	v_add_f32_e32 v40, v40, v41
	v_add_f32_e32 v42, v42, v43
	v_add_f32_e32 v36, v36, v38
	v_add_f32_e32 v40, v40, v42
	v_add_f32_e32 v36, v36, v40
	v_mfma_f32_32x32x16_bf16 v[4:19], v[152:155], v[168:171], v[4:19]
	v_fma_f32 v44, v44, s33, -v107
	v_fma_f32 v45, v45, s33, -v107
	v_fma_f32 v46, v46, s33, -v107
	v_fma_f32 v47, v47, s33, -v107
	v_fma_f32 v48, v48, s33, -v107
	v_fma_f32 v49, v49, s33, -v107
	v_fma_f32 v50, v50, s33, -v107
	v_fma_f32 v51, v51, s33, -v107
	v_exp_f32_e32 v44, v44
	v_exp_f32_e32 v45, v45
	v_exp_f32_e32 v46, v46
	v_exp_f32_e32 v47, v47
	v_exp_f32_e32 v48, v48
	v_exp_f32_e32 v49, v49
	v_exp_f32_e32 v50, v50
	v_exp_f32_e32 v51, v51
	v_cvt_pk_bf16_f32 v176, v44, v45
	v_cvt_pk_bf16_f32 v177, v46, v47
	v_cvt_pk_bf16_f32 v178, v48, v49
	v_cvt_pk_bf16_f32 v179, v50, v51
	v_add_f32_e32 v44, v44, v45
	v_add_f32_e32 v46, v46, v47
	v_add_f32_e32 v48, v48, v49
	v_add_f32_e32 v50, v50, v51
	v_add_f32_e32 v44, v44, v46
	v_add_f32_e32 v48, v48, v50
	v_add_f32_e32 v44, v44, v48
	v_add_f32_e32 v52, v52, v60
	v_add_f32_e32 v36, v36, v44
	v_add_f32_e32 v52, v52, v36
	v_fma_f32 v36, v130, v114, v52
	v_mfma_f32_32x32x16_bf16 v[20:35], v[140:143], v[172:175], v[20:35]
	v_mfma_f32_32x32x16_bf16 v[4:19], v[156:159], v[172:175], v[4:19]
	v_mfma_f32_32x32x16_bf16 v[20:35], v[144:147], v[176:179], v[20:35]
	v_mfma_f32_32x32x16_bf16 v[4:19], v[160:163], v[176:179], v[4:19]
	s_add_i32 s27, s27, 1
	s_add_i32 s26, s26, -1
	s_cmp_lg_u32 s26, -1
	s_cbranch_scc0 .Lu96_exit

.Lu96_1_383:
	ds_read_b128 v[132:135], v194 offset:16384
	ds_read_b128 v[136:139], v195 offset:16384
	ds_read_b128 v[140:143], v196 offset:16384
	ds_read_b128 v[144:147], v197 offset:16384
	ds_read_b128 v[148:151], v198 offset:16384
	ds_read_b128 v[152:155], v199 offset:16384
	ds_read_b128 v[156:159], v194 offset:24576
	ds_read_b128 v[160:163], v195 offset:24576
	ds_read_b128 v[164:167], v196 offset:24576
	ds_read_b128 v[168:171], v197 offset:24576
	ds_read_b128 v[172:175], v198 offset:24576
	ds_read_b128 v[176:179], v199 offset:24576
	s_waitcnt lgkmcnt(11)
	v_mfma_f32_32x32x16_bf16 v[52:67], v[132:135], v[68:71], 0
	s_waitcnt lgkmcnt(10)
	v_mfma_f32_32x32x16_bf16 v[52:67], v[136:139], v[72:75], v[52:67]
	s_waitcnt lgkmcnt(9)
	v_mfma_f32_32x32x16_bf16 v[52:67], v[140:143], v[76:79], v[52:67]
	s_waitcnt lgkmcnt(8)
	v_mfma_f32_32x32x16_bf16 v[52:67], v[144:147], v[80:83], v[52:67]
	s_waitcnt lgkmcnt(7)
	v_mfma_f32_32x32x16_bf16 v[52:67], v[148:151], v[84:87], v[52:67]
	s_waitcnt lgkmcnt(6)
	v_mfma_f32_32x32x16_bf16 v[52:67], v[152:155], v[88:91], v[52:67]
	s_waitcnt lgkmcnt(0)
	v_mfma_f32_32x32x16_bf16 v[36:51], v[156:159], v[68:71], 0
	ds_read_b64 v[132:133], v200 offset:8192
	ds_read_b64 v[134:135], v201 offset:8192
	v_mfma_f32_32x32x16_bf16 v[36:51], v[160:163], v[72:75], v[36:51]
	ds_read_b64 v[136:137], v202 offset:8192
	ds_read_b64 v[138:139], v203 offset:8192
	v_mfma_f32_32x32x16_bf16 v[36:51], v[164:167], v[76:79], v[36:51]
	ds_read_b64 v[140:141], v204 offset:8192
	ds_read_b64 v[142:143], v205 offset:8192
	v_mfma_f32_32x32x16_bf16 v[36:51], v[168:171], v[80:83], v[36:51]
	ds_read_b64 v[144:145], v206 offset:8192
	ds_read_b64 v[146:147], v207 offset:8192
	v_mfma_f32_32x32x16_bf16 v[36:51], v[172:175], v[84:87], v[36:51]
	v_mfma_f32_32x32x16_bf16 v[36:51], v[176:179], v[88:91], v[36:51]
	ds_read_b64 v[156:157], v204 offset:12288
	ds_read_b64 v[158:159], v205 offset:12288
	ds_read_b64 v[160:161], v206 offset:12288
	ds_read_b64 v[162:163], v207 offset:12288
	ds_read_b64 v[152:153], v202 offset:12288
	ds_read_b64 v[154:155], v203 offset:12288
	ds_read_b64 v[148:149], v200 offset:12288
	ds_read_b64 v[150:151], v201 offset:12288
	v_max3_f32 v107, v52, v53, v54
	v_max3_f32 v107, v107, v55, v56
	v_max3_f32 v107, v107, v57, v58
	v_max3_f32 v107, v107, v59, v60
	v_max3_f32 v107, v107, v61, v62
	v_max3_f32 v107, v107, v63, v64
	v_max3_f32 v107, v107, v65, v66
	v_max_f32_e32 v107, v107, v67
	v_max3_f32 v114, v36, v37, v38
	v_max3_f32 v114, v114, v39, v40
	v_max3_f32 v114, v114, v41, v42
	v_max3_f32 v114, v114, v43, v44
	v_max3_f32 v114, v114, v45, v46
	v_max3_f32 v114, v114, v47, v48
	v_max3_f32 v114, v114, v49, v50
	v_max3_f32 v107, v107, v114, v51
	v_mul_f32_e32 v107, s33, v107
	v_mov_b32_e32 v172, v107
	s_nop 1
	v_permlane32_swap_b32 v107, v172
	s_nop 1
	v_max3_f32 v107, v131, v107, v172
	v_sub_f32_e32 v114, v131, v107
	v_exp_f32_e32 v114, v114
	v_cmp_neq_f32_e32 vcc, v107, v131
	s_cbranch_vccz .Lat96u1_keep
	v_pk_mul_f32 v[34:35], v[34:35], v[114:115] op_sel_hi:[1,0]
	v_pk_mul_f32 v[32:33], v[32:33], v[114:115] op_sel_hi:[1,0]
	v_pk_mul_f32 v[30:31], v[30:31], v[114:115] op_sel_hi:[1,0]
	v_pk_mul_f32 v[28:29], v[28:29], v[114:115] op_sel_hi:[1,0]
	v_pk_mul_f32 v[26:27], v[26:27], v[114:115] op_sel_hi:[1,0]
	v_pk_mul_f32 v[24:25], v[24:25], v[114:115] op_sel_hi:[1,0]
	v_pk_mul_f32 v[22:23], v[22:23], v[114:115] op_sel_hi:[1,0]
	v_pk_mul_f32 v[20:21], v[20:21], v[114:115] op_sel_hi:[1,0]
	v_pk_mul_f32 v[18:19], v[18:19], v[114:115] op_sel_hi:[1,0]
	v_pk_mul_f32 v[16:17], v[16:17], v[114:115] op_sel_hi:[1,0]
	v_pk_mul_f32 v[14:15], v[14:15], v[114:115] op_sel_hi:[1,0]
	v_pk_mul_f32 v[12:13], v[12:13], v[114:115] op_sel_hi:[1,0]
	v_pk_mul_f32 v[10:11], v[10:11], v[114:115] op_sel_hi:[1,0]
	v_pk_mul_f32 v[8:9], v[8:9], v[114:115] op_sel_hi:[1,0]
	v_pk_mul_f32 v[6:7], v[6:7], v[114:115] op_sel_hi:[1,0]
	v_pk_mul_f32 v[4:5], v[4:5], v[114:115] op_sel_hi:[1,0]
.Lat96u1_keep:
	v_fma_f32 v52, v52, s33, -v107
	v_fma_f32 v53, v53, s33, -v107
	v_fma_f32 v54, v54, s33, -v107
	v_fma_f32 v55, v55, s33, -v107
	v_fma_f32 v56, v56, s33, -v107
	v_fma_f32 v57, v57, s33, -v107
	v_fma_f32 v58, v58, s33, -v107
	v_fma_f32 v59, v59, s33, -v107
	v_exp_f32_e32 v52, v52
	v_exp_f32_e32 v53, v53
	v_exp_f32_e32 v54, v54
	v_exp_f32_e32 v55, v55
	v_exp_f32_e32 v56, v56
	v_exp_f32_e32 v57, v57
	v_exp_f32_e32 v58, v58
	v_exp_f32_e32 v59, v59
	v_cvt_pk_bf16_f32 v164, v52, v53
	v_cvt_pk_bf16_f32 v165, v54, v55
	v_cvt_pk_bf16_f32 v166, v56, v57
	v_cvt_pk_bf16_f32 v167, v58, v59
	v_add_f32_e32 v52, v52, v53
	v_add_f32_e32 v54, v54, v55
	v_add_f32_e32 v56, v56, v57
	v_add_f32_e32 v58, v58, v59
	v_add_f32_e32 v52, v52, v54
	v_add_f32_e32 v56, v56, v58
	v_add_f32_e32 v52, v52, v56
	s_cmp_ge_i32 s27, s5
	s_cbranch_scc1 .Lat96u1_nodma
	s_cmp_eq_u32 s4, s0
	s_cselect_b64 s[2:3], -1, 0
	s_and_b64 vcc, s[24:25], s[2:3]
	s_add_i32 m0, s98, 0x0
	v_cndmask_b32_e32 v59, v109, v95, vcc
	v_cndmask_b32_e32 v58, v108, v94, vcc
	v_cndmask_b32_e32 v57, v111, v97, vcc
	v_cndmask_b32_e32 v56, v110, v96, vcc
	global_load_lds_dwordx4 v[58:59], off
	s_add_i32 m0, s98, 0x400
	v_cndmask_b32_e32 v55, v113, v105, vcc
	v_cndmask_b32_e32 v54, v112, v104, vcc
	global_load_lds_dwordx4 v[56:57], off
	s_add_i32 m0, s99, 0x0
	v_cndmask_b32_e32 v106, v106, v102, vcc
	global_load_lds_dwordx4 v[54:55], off
	v_cndmask_b32_e32 v2, v2, v100, vcc
	v_lshl_add_u64 v[108:109], v[2:3], 1, v[58:59]
	v_lshlrev_b32_e32 v53, 1, v106
	v_add_co_u32_e32 v110, vcc, v53, v56
	s_nop 1
	v_addc_co_u32_e32 v111, vcc, 0, v57, vcc
	v_lshl_add_u64 v[112:113], v[54:55], 0, s[82:83]
	s_add_i32 s4, s4, 1

.Lu96_2_383:
	ds_read_b128 v[132:135], v194 offset:32768
	ds_read_b128 v[136:139], v195 offset:32768
	ds_read_b128 v[140:143], v196 offset:32768
	ds_read_b128 v[144:147], v197 offset:32768
	ds_read_b128 v[148:151], v198 offset:32768
	ds_read_b128 v[152:155], v199 offset:32768
	ds_read_b128 v[156:159], v194 offset:40960
	ds_read_b128 v[160:163], v195 offset:40960
	ds_read_b128 v[164:167], v196 offset:40960
	ds_read_b128 v[168:171], v197 offset:40960
	ds_read_b128 v[172:175], v198 offset:40960
	ds_read_b128 v[176:179], v199 offset:40960
	s_waitcnt lgkmcnt(11)
	v_mfma_f32_32x32x16_bf16 v[52:67], v[132:135], v[68:71], 0
	s_waitcnt lgkmcnt(10)
	v_mfma_f32_32x32x16_bf16 v[52:67], v[136:139], v[72:75], v[52:67]
	s_waitcnt lgkmcnt(9)
	v_mfma_f32_32x32x16_bf16 v[52:67], v[140:143], v[76:79], v[52:67]
	s_waitcnt lgkmcnt(8)
	v_mfma_f32_32x32x16_bf16 v[52:67], v[144:147], v[80:83], v[52:67]
	s_waitcnt lgkmcnt(7)
	v_mfma_f32_32x32x16_bf16 v[52:67], v[148:151], v[84:87], v[52:67]
	s_waitcnt lgkmcnt(6)
	v_mfma_f32_32x32x16_bf16 v[52:67], v[152:155], v[88:91], v[52:67]
	s_waitcnt lgkmcnt(0)
	v_mfma_f32_32x32x16_bf16 v[36:51], v[156:159], v[68:71], 0
	ds_read_b64 v[132:133], v200 offset:16384
	ds_read_b64 v[134:135], v201 offset:16384
	v_mfma_f32_32x32x16_bf16 v[36:51], v[160:163], v[72:75], v[36:51]
	ds_read_b64 v[136:137], v202 offset:16384
	ds_read_b64 v[138:139], v203 offset:16384
	v_mfma_f32_32x32x16_bf16 v[36:51], v[164:167], v[76:79], v[36:51]
	ds_read_b64 v[140:141], v204 offset:16384
	ds_read_b64 v[142:143], v205 offset:16384
	v_mfma_f32_32x32x16_bf16 v[36:51], v[168:171], v[80:83], v[36:51]
	ds_read_b64 v[144:145], v206 offset:16384
	ds_read_b64 v[146:147], v207 offset:16384
	v_mfma_f32_32x32x16_bf16 v[36:51], v[172:175], v[84:87], v[36:51]
	v_mfma_f32_32x32x16_bf16 v[36:51], v[176:179], v[88:91], v[36:51]
	ds_read_b64 v[156:157], v204 offset:20480
	ds_read_b64 v[158:159], v205 offset:20480
	ds_read_b64 v[160:161], v206 offset:20480
	ds_read_b64 v[162:163], v207 offset:20480
	ds_read_b64 v[152:153], v202 offset:20480
	ds_read_b64 v[154:155], v203 offset:20480
	ds_read_b64 v[148:149], v200 offset:20480
	ds_read_b64 v[150:151], v201 offset:20480
	v_max3_f32 v107, v52, v53, v54
	v_max3_f32 v107, v107, v55, v56
	v_max3_f32 v107, v107, v57, v58
	v_max3_f32 v107, v107, v59, v60
	v_max3_f32 v107, v107, v61, v62
	v_max3_f32 v107, v107, v63, v64
	v_max3_f32 v107, v107, v65, v66
	v_max_f32_e32 v107, v107, v67
	v_max3_f32 v114, v36, v37, v38
	v_max3_f32 v114, v114, v39, v40
	v_max3_f32 v114, v114, v41, v42
	v_max3_f32 v114, v114, v43, v44
	v_max3_f32 v114, v114, v45, v46
	v_max3_f32 v114, v114, v47, v48
	v_max3_f32 v114, v114, v49, v50
	v_max3_f32 v107, v107, v114, v51
	v_mul_f32_e32 v107, s33, v107
	v_mov_b32_e32 v172, v107
	s_nop 1
	v_permlane32_swap_b32 v107, v172
	s_nop 1
	v_max3_f32 v107, v131, v107, v172
	v_sub_f32_e32 v114, v131, v107
	v_exp_f32_e32 v114, v114
	v_cmp_neq_f32_e32 vcc, v107, v131
	s_cbranch_vccz .Lat96u2_keep
	v_pk_mul_f32 v[34:35], v[34:35], v[114:115] op_sel_hi:[1,0]
	v_pk_mul_f32 v[32:33], v[32:33], v[114:115] op_sel_hi:[1,0]
	v_pk_mul_f32 v[30:31], v[30:31], v[114:115] op_sel_hi:[1,0]
	v_pk_mul_f32 v[28:29], v[28:29], v[114:115] op_sel_hi:[1,0]
	v_pk_mul_f32 v[26:27], v[26:27], v[114:115] op_sel_hi:[1,0]
	v_pk_mul_f32 v[24:25], v[24:25], v[114:115] op_sel_hi:[1,0]
	v_pk_mul_f32 v[22:23], v[22:23], v[114:115] op_sel_hi:[1,0]
	v_pk_mul_f32 v[20:21], v[20:21], v[114:115] op_sel_hi:[1,0]
	v_pk_mul_f32 v[18:19], v[18:19], v[114:115] op_sel_hi:[1,0]
	v_pk_mul_f32 v[16:17], v[16:17], v[114:115] op_sel_hi:[1,0]
	v_pk_mul_f32 v[14:15], v[14:15], v[114:115] op_sel_hi:[1,0]
	v_pk_mul_f32 v[12:13], v[12:13], v[114:115] op_sel_hi:[1,0]
	v_pk_mul_f32 v[10:11], v[10:11], v[114:115] op_sel_hi:[1,0]
	v_pk_mul_f32 v[8:9], v[8:9], v[114:115] op_sel_hi:[1,0]
	v_pk_mul_f32 v[6:7], v[6:7], v[114:115] op_sel_hi:[1,0]
	v_pk_mul_f32 v[4:5], v[4:5], v[114:115] op_sel_hi:[1,0]
.Lat96u2_keep:
	v_fma_f32 v52, v52, s33, -v107
	v_fma_f32 v53, v53, s33, -v107
	v_fma_f32 v54, v54, s33, -v107
	v_fma_f32 v55, v55, s33, -v107
	v_fma_f32 v56, v56, s33, -v107
	v_fma_f32 v57, v57, s33, -v107
	v_fma_f32 v58, v58, s33, -v107
	v_fma_f32 v59, v59, s33, -v107
	v_exp_f32_e32 v52, v52
	v_exp_f32_e32 v53, v53
	v_exp_f32_e32 v54, v54
	v_exp_f32_e32 v55, v55
	v_exp_f32_e32 v56, v56
	v_exp_f32_e32 v57, v57
	v_exp_f32_e32 v58, v58
	v_exp_f32_e32 v59, v59
	v_cvt_pk_bf16_f32 v164, v52, v53
	v_cvt_pk_bf16_f32 v165, v54, v55
	v_cvt_pk_bf16_f32 v166, v56, v57
	v_cvt_pk_bf16_f32 v167, v58, v59
	v_add_f32_e32 v52, v52, v53
	v_add_f32_e32 v54, v54, v55
	v_add_f32_e32 v56, v56, v57
	v_add_f32_e32 v58, v58, v59
	v_add_f32_e32 v52, v52, v54
	v_add_f32_e32 v56, v56, v58
	v_add_f32_e32 v52, v52, v56
	s_cmp_ge_i32 s27, s5
	s_cbranch_scc1 .Lat96u2_nodma
	s_cmp_eq_u32 s4, s0
	s_cselect_b64 s[2:3], -1, 0
	s_and_b64 vcc, s[24:25], s[2:3]
	s_add_i32 m0, s98, 0x4000
	v_cndmask_b32_e32 v59, v109, v95, vcc
	v_cndmask_b32_e32 v58, v108, v94, vcc
	v_cndmask_b32_e32 v57, v111, v97, vcc
	v_cndmask_b32_e32 v56, v110, v96, vcc
	global_load_lds_dwordx4 v[58:59], off
	s_add_i32 m0, s98, 0x4400
	v_cndmask_b32_e32 v55, v113, v105, vcc
	v_cndmask_b32_e32 v54, v112, v104, vcc
	global_load_lds_dwordx4 v[56:57], off
	s_add_i32 m0, s99, 0x2000
	v_cndmask_b32_e32 v106, v106, v102, vcc
	global_load_lds_dwordx4 v[54:55], off
	v_cndmask_b32_e32 v2, v2, v100, vcc
	v_lshl_add_u64 v[108:109], v[2:3], 1, v[58:59]
	v_lshlrev_b32_e32 v53, 1, v106
	v_add_co_u32_e32 v110, vcc, v53, v56
	s_nop 1
	v_addc_co_u32_e32 v111, vcc, 0, v57, vcc
	v_lshl_add_u64 v[112:113], v[54:55], 0, s[82:83]
	s_add_i32 s4, s4, 1

.Lu96_3_383:
	ds_read_b128 v[132:135], v194 offset:49152
	ds_read_b128 v[136:139], v195 offset:49152
	ds_read_b128 v[140:143], v196 offset:49152
	ds_read_b128 v[144:147], v197 offset:49152
	ds_read_b128 v[148:151], v198 offset:49152
	ds_read_b128 v[152:155], v199 offset:49152
	ds_read_b128 v[156:159], v194 offset:57344
	ds_read_b128 v[160:163], v195 offset:57344
	ds_read_b128 v[164:167], v196 offset:57344
	ds_read_b128 v[168:171], v197 offset:57344
	ds_read_b128 v[172:175], v198 offset:57344
	ds_read_b128 v[176:179], v199 offset:57344
	s_waitcnt lgkmcnt(11)
	v_mfma_f32_32x32x16_bf16 v[52:67], v[132:135], v[68:71], 0
	s_waitcnt lgkmcnt(10)
	v_mfma_f32_32x32x16_bf16 v[52:67], v[136:139], v[72:75], v[52:67]
	s_waitcnt lgkmcnt(9)
	v_mfma_f32_32x32x16_bf16 v[52:67], v[140:143], v[76:79], v[52:67]
	s_waitcnt lgkmcnt(8)
	v_mfma_f32_32x32x16_bf16 v[52:67], v[144:147], v[80:83], v[52:67]
	s_waitcnt lgkmcnt(7)
	v_mfma_f32_32x32x16_bf16 v[52:67], v[148:151], v[84:87], v[52:67]
	s_waitcnt lgkmcnt(6)
	v_mfma_f32_32x32x16_bf16 v[52:67], v[152:155], v[88:91], v[52:67]
	s_waitcnt lgkmcnt(0)
	v_mfma_f32_32x32x16_bf16 v[36:51], v[156:159], v[68:71], 0
	ds_read_b64 v[132:133], v200 offset:24576
	ds_read_b64 v[134:135], v201 offset:24576
	v_mfma_f32_32x32x16_bf16 v[36:51], v[160:163], v[72:75], v[36:51]
	ds_read_b64 v[136:137], v202 offset:24576
	ds_read_b64 v[138:139], v203 offset:24576
	v_mfma_f32_32x32x16_bf16 v[36:51], v[164:167], v[76:79], v[36:51]
	ds_read_b64 v[140:141], v204 offset:24576
	ds_read_b64 v[142:143], v205 offset:24576
	v_mfma_f32_32x32x16_bf16 v[36:51], v[168:171], v[80:83], v[36:51]
	ds_read_b64 v[144:145], v206 offset:24576
	ds_read_b64 v[146:147], v207 offset:24576
	v_mfma_f32_32x32x16_bf16 v[36:51], v[172:175], v[84:87], v[36:51]
	v_mfma_f32_32x32x16_bf16 v[36:51], v[176:179], v[88:91], v[36:51]
	ds_read_b64 v[156:157], v204 offset:28672
	ds_read_b64 v[158:159], v205 offset:28672
	ds_read_b64 v[160:161], v206 offset:28672
	ds_read_b64 v[162:163], v207 offset:28672
	ds_read_b64 v[152:153], v202 offset:28672
	ds_read_b64 v[154:155], v203 offset:28672
	ds_read_b64 v[148:149], v200 offset:28672
	ds_read_b64 v[150:151], v201 offset:28672
	v_max3_f32 v107, v52, v53, v54
	v_max3_f32 v107, v107, v55, v56
	v_max3_f32 v107, v107, v57, v58
	v_max3_f32 v107, v107, v59, v60
	v_max3_f32 v107, v107, v61, v62
	v_max3_f32 v107, v107, v63, v64
	v_max3_f32 v107, v107, v65, v66
	v_max_f32_e32 v107, v107, v67
	v_max3_f32 v114, v36, v37, v38
	v_max3_f32 v114, v114, v39, v40
	v_max3_f32 v114, v114, v41, v42
	v_max3_f32 v114, v114, v43, v44
	v_max3_f32 v114, v114, v45, v46
	v_max3_f32 v114, v114, v47, v48
	v_max3_f32 v114, v114, v49, v50
	v_max3_f32 v107, v107, v114, v51
	v_mul_f32_e32 v107, s33, v107
	v_mov_b32_e32 v172, v107
	s_nop 1
	v_permlane32_swap_b32 v107, v172
	s_nop 1
	v_max3_f32 v107, v131, v107, v172
	v_sub_f32_e32 v114, v131, v107
	v_exp_f32_e32 v114, v114
	v_cmp_neq_f32_e32 vcc, v107, v131
	s_cbranch_vccz .Lat96u3_keep
	v_pk_mul_f32 v[34:35], v[34:35], v[114:115] op_sel_hi:[1,0]
	v_pk_mul_f32 v[32:33], v[32:33], v[114:115] op_sel_hi:[1,0]
	v_pk_mul_f32 v[30:31], v[30:31], v[114:115] op_sel_hi:[1,0]
	v_pk_mul_f32 v[28:29], v[28:29], v[114:115] op_sel_hi:[1,0]
	v_pk_mul_f32 v[26:27], v[26:27], v[114:115] op_sel_hi:[1,0]
	v_pk_mul_f32 v[24:25], v[24:25], v[114:115] op_sel_hi:[1,0]
	v_pk_mul_f32 v[22:23], v[22:23], v[114:115] op_sel_hi:[1,0]
	v_pk_mul_f32 v[20:21], v[20:21], v[114:115] op_sel_hi:[1,0]
	v_pk_mul_f32 v[18:19], v[18:19], v[114:115] op_sel_hi:[1,0]
	v_pk_mul_f32 v[16:17], v[16:17], v[114:115] op_sel_hi:[1,0]
	v_pk_mul_f32 v[14:15], v[14:15], v[114:115] op_sel_hi:[1,0]
	v_pk_mul_f32 v[12:13], v[12:13], v[114:115] op_sel_hi:[1,0]
	v_pk_mul_f32 v[10:11], v[10:11], v[114:115] op_sel_hi:[1,0]
	v_pk_mul_f32 v[8:9], v[8:9], v[114:115] op_sel_hi:[1,0]
	v_pk_mul_f32 v[6:7], v[6:7], v[114:115] op_sel_hi:[1,0]
	v_pk_mul_f32 v[4:5], v[4:5], v[114:115] op_sel_hi:[1,0]
.Lat96u3_keep:
	v_fma_f32 v52, v52, s33, -v107
	v_fma_f32 v53, v53, s33, -v107
	v_fma_f32 v54, v54, s33, -v107
	v_fma_f32 v55, v55, s33, -v107
	v_fma_f32 v56, v56, s33, -v107
	v_fma_f32 v57, v57, s33, -v107
	v_fma_f32 v58, v58, s33, -v107
	v_fma_f32 v59, v59, s33, -v107
	v_exp_f32_e32 v52, v52
	v_exp_f32_e32 v53, v53
	v_exp_f32_e32 v54, v54
	v_exp_f32_e32 v55, v55
	v_exp_f32_e32 v56, v56
	v_exp_f32_e32 v57, v57
	v_exp_f32_e32 v58, v58
	v_exp_f32_e32 v59, v59
	v_cvt_pk_bf16_f32 v164, v52, v53
	v_cvt_pk_bf16_f32 v165, v54, v55
	v_cvt_pk_bf16_f32 v166, v56, v57
	v_cvt_pk_bf16_f32 v167, v58, v59
	v_add_f32_e32 v52, v52, v53
	v_add_f32_e32 v54, v54, v55
	v_add_f32_e32 v56, v56, v57
	v_add_f32_e32 v58, v58, v59
	v_add_f32_e32 v52, v52, v54
	v_add_f32_e32 v56, v56, v58
	v_add_f32_e32 v52, v52, v56
	s_cmp_ge_i32 s27, s5
	s_cbranch_scc1 .Lat96u3_nodma
	s_cmp_eq_u32 s4, s0
	s_cselect_b64 s[2:3], -1, 0
	s_and_b64 vcc, s[24:25], s[2:3]
	s_add_i32 m0, s98, 0x8000
	v_cndmask_b32_e32 v59, v109, v95, vcc
	v_cndmask_b32_e32 v58, v108, v94, vcc
	v_cndmask_b32_e32 v57, v111, v97, vcc
	v_cndmask_b32_e32 v56, v110, v96, vcc
	global_load_lds_dwordx4 v[58:59], off
	s_add_i32 m0, s98, 0x8400
	v_cndmask_b32_e32 v55, v113, v105, vcc
	v_cndmask_b32_e32 v54, v112, v104, vcc
	global_load_lds_dwordx4 v[56:57], off
	s_add_i32 m0, s99, 0x4000
	v_cndmask_b32_e32 v106, v106, v102, vcc
	global_load_lds_dwordx4 v[54:55], off
	v_cndmask_b32_e32 v2, v2, v100, vcc
	v_lshl_add_u64 v[108:109], v[2:3], 1, v[58:59]
	v_lshlrev_b32_e32 v53, 1, v106
	v_add_co_u32_e32 v110, vcc, v53, v56
	s_nop 1
	v_addc_co_u32_e32 v111, vcc, 0, v57, vcc
	v_lshl_add_u64 v[112:113], v[54:55], 0, s[82:83]
	s_add_i32 s4, s4, 1

.Lu96_exit:
.LBB0_386:
	v_xor_b32_e32 v2, 32, v229
	v_cmp_lt_i32_e32 vcc, v2, v231
	v_mov_b32_e32 v99, v3
	s_waitcnt vmcnt(0) lgkmcnt(0)
	v_cndmask_b32_e32 v2, v229, v2, vcc
	v_lshlrev_b32_e32 v2, 2, v2
	ds_bpermute_b32 v2, v2, v36
	s_barrier
	s_waitcnt lgkmcnt(0)
	s_mov_b64 s[28:29], 0
	v_add_f32_e32 v2, v36, v2
	v_div_scale_f32 v36, s[2:3], v2, v2, 1.0
	v_rcp_f32_e32 v37, v36
	v_div_scale_f32 v38, vcc, 1.0, v2, 1.0
	v_readlane_b32 s2, v251, 52
	v_fma_f32 v39, -v36, v37, 1.0
	v_fmac_f32_e32 v37, v39, v37
	v_mul_f32_e32 v39, v38, v37
	v_fma_f32 v40, -v36, v39, v38
	v_fmac_f32_e32 v39, v40, v37
	v_fma_f32 v36, -v36, v39, v38
	v_div_fmas_f32 v36, v36, v37, v39
	v_div_fixup_f32 v2, v36, v2, 1.0
	v_lshlrev_b64 v[36:37], 11, v[92:93]
	v_readlane_b32 s3, v251, 53
	v_pk_mul_f32 v[4:5], v[4:5], v[2:3] op_sel_hi:[1,0]
	v_pk_mul_f32 v[6:7], v[6:7], v[2:3] op_sel_hi:[1,0]
	v_pk_mul_f32 v[8:9], v[8:9], v[2:3] op_sel_hi:[1,0]
	v_pk_mul_f32 v[10:11], v[10:11], v[2:3] op_sel_hi:[1,0]
	v_pk_mul_f32 v[12:13], v[12:13], v[2:3] op_sel_hi:[1,0]
	v_pk_mul_f32 v[14:15], v[14:15], v[2:3] op_sel_hi:[1,0]
	v_pk_mul_f32 v[16:17], v[16:17], v[2:3] op_sel_hi:[1,0]
	v_pk_mul_f32 v[18:19], v[18:19], v[2:3] op_sel_hi:[1,0]
	v_pk_mul_f32 v[20:21], v[20:21], v[2:3] op_sel_hi:[1,0]
	v_pk_mul_f32 v[22:23], v[22:23], v[2:3] op_sel_hi:[1,0]
	v_pk_mul_f32 v[24:25], v[24:25], v[2:3] op_sel_hi:[1,0]
	v_pk_mul_f32 v[26:27], v[26:27], v[2:3] op_sel_hi:[1,0]
	v_pk_mul_f32 v[28:29], v[28:29], v[2:3] op_sel_hi:[1,0]
	v_pk_mul_f32 v[30:31], v[30:31], v[2:3] op_sel_hi:[1,0]
	v_pk_mul_f32 v[32:33], v[32:33], v[2:3] op_sel_hi:[1,0]
	v_pk_mul_f32 v[34:35], v[34:35], v[2:3] op_sel_hi:[1,0]
	v_lshl_add_u64 v[36:37], s[2:3], 0, v[36:37]
	v_cvt_pk_bf16_f32 v40, v20, v21
	v_cvt_pk_bf16_f32 v41, v22, v23
	v_cvt_pk_bf16_f32 v42, v24, v25
	v_cvt_pk_bf16_f32 v43, v26, v27
	v_cvt_pk_bf16_f32 v44, v28, v29
	v_cvt_pk_bf16_f32 v45, v30, v31
	v_cvt_pk_bf16_f32 v46, v32, v33
	v_cvt_pk_bf16_f32 v47, v34, v35
	v_cvt_pk_bf16_f32 v48, v4, v5
	v_cvt_pk_bf16_f32 v49, v6, v7
	v_cvt_pk_bf16_f32 v50, v8, v9
	v_cvt_pk_bf16_f32 v51, v10, v11
	v_cvt_pk_bf16_f32 v52, v12, v13
	v_cvt_pk_bf16_f32 v53, v14, v15
	v_cvt_pk_bf16_f32 v54, v16, v17
	v_cvt_pk_bf16_f32 v55, v18, v19
	v_lshl_add_u64 v[36:37], v[98:99], 1, v[36:37]
	s_nop 1
	v_permlane32_swap_b32 v40, v42
	v_permlane32_swap_b32 v41, v43
	v_permlane32_swap_b32 v44, v46
	v_permlane32_swap_b32 v45, v47
	v_permlane32_swap_b32 v48, v50
	v_permlane32_swap_b32 v49, v51
	v_permlane32_swap_b32 v52, v54
	v_permlane32_swap_b32 v53, v55
	s_nop 1
	global_store_dwordx4 v[36:37], v[40:43], off
	global_store_dwordx4 v[36:37], v[44:47], off offset:32
	global_store_dwordx4 v[36:37], v[48:51], off offset:64
	global_store_dwordx4 v[36:37], v[52:55], off offset:96
	s_barrier
